# P7 prompt item: waves 4-7 delayed by s_sleep 40 after staging barrier (stagger SIMD partner waves so softmax VALU overlaps partner QK/PV)
# speedup vs baseline: 1.0056x; 1.0056x over previous
.LBB0_1057:
	s_andn2_b64 vcc, exec, s[26:27]
	s_cbranch_vccnz .LBB0_1051
	s_ashr_i32 s26, s31, 5
	s_lshl_b32 s27, s26, 8
	s_bfe_u32 s33, s31, 0x20003
	v_or_b32_e32 v0, s27, v108
	v_or_b32_e32 v8, s27, v125
	v_or_b32_e32 v16, s27, v113
	v_or_b32_e32 v24, s27, v127
	v_or_b32_e32 v32, s27, v116
	s_lshl_b32 s2, s33, 8
	v_ashrrev_i32_e32 v1, 31, v0
	v_ashrrev_i32_e32 v9, 31, v8
	v_ashrrev_i32_e32 v17, 31, v16
	v_ashrrev_i32_e32 v25, 31, v24
	v_ashrrev_i32_e32 v33, 31, v32
	v_or_b32_e32 v54, s27, v129
	v_or_b32_e32 v62, s27, v119
	v_lshlrev_b64 v[0:1], 10, v[0:1]
	v_lshl_or_b32 v40, v107, 1, s2
	v_lshlrev_b64 v[8:9], 10, v[8:9]
	v_lshlrev_b64 v[16:17], 10, v[16:17]
	v_lshlrev_b64 v[24:25], 10, v[24:25]
	v_lshlrev_b64 v[32:33], 10, v[32:33]
	v_ashrrev_i32_e32 v55, 31, v54
	v_ashrrev_i32_e32 v63, 31, v62
	v_add_u32_e32 v70, s27, v131
	v_or_b32_e32 v0, v0, v40
	v_or_b32_e32 v8, v8, v40
	v_or_b32_e32 v16, v16, v40
	v_or_b32_e32 v24, v24, v40
	v_or_b32_e32 v32, v32, v40
	v_lshlrev_b64 v[54:55], 10, v[54:55]
	v_lshlrev_b64 v[62:63], 10, v[62:63]
	v_ashrrev_i32_e32 v71, 31, v70
	v_lshl_add_u64 v[2:3], s[14:15], 0, v[0:1]
	v_lshl_add_u64 v[4:5], s[16:17], 0, v[0:1]
	v_lshl_add_u64 v[10:11], s[14:15], 0, v[8:9]
	v_lshl_add_u64 v[12:13], s[16:17], 0, v[8:9]
	v_lshl_add_u64 v[18:19], s[14:15], 0, v[16:17]
	v_lshl_add_u64 v[20:21], s[16:17], 0, v[16:17]
	v_lshl_add_u64 v[26:27], s[14:15], 0, v[24:25]
	v_lshl_add_u64 v[28:29], s[16:17], 0, v[24:25]
	v_lshl_add_u64 v[34:35], s[14:15], 0, v[32:33]
	v_lshl_add_u64 v[36:37], s[16:17], 0, v[32:33]
	v_or_b32_e32 v54, v54, v40
	v_or_b32_e32 v62, v62, v40
	v_lshlrev_b64 v[74:75], 10, v[70:71]
	s_barrier
	global_load_dwordx4 v[0:3], v[2:3], off
	s_nop 0
	global_load_dwordx4 v[4:7], v[4:5], off
	s_nop 0
	global_load_dwordx4 v[8:11], v[10:11], off
	s_nop 0
	global_load_dwordx4 v[12:15], v[12:13], off
	s_nop 0
	global_load_dwordx4 v[16:19], v[18:19], off
	s_nop 0
	global_load_dwordx4 v[20:23], v[20:21], off
	s_nop 0
	global_load_dwordx4 v[24:27], v[26:27], off
	s_nop 0
	global_load_dwordx4 v[28:31], v[28:29], off
	s_nop 0
	global_load_dwordx4 v[32:35], v[34:35], off
	s_nop 0
	global_load_dwordx4 v[36:39], v[36:37], off
	v_lshl_add_u64 v[56:57], s[14:15], 0, v[54:55]
	v_lshl_add_u64 v[58:59], s[16:17], 0, v[54:55]
	v_lshl_add_u64 v[64:65], s[14:15], 0, v[62:63]
	v_lshl_add_u64 v[66:67], s[16:17], 0, v[62:63]
	v_or_b32_e32 v74, v74, v40
	global_load_dwordx4 v[54:57], v[56:57], off
	s_nop 0
	global_load_dwordx4 v[58:61], v[58:59], off
	s_nop 0
	global_load_dwordx4 v[62:65], v[64:65], off
	s_nop 0
	global_load_dwordx4 v[66:69], v[66:67], off
	v_lshl_add_u64 v[70:71], s[14:15], 0, v[74:75]
	global_load_dwordx4 v[70:73], v[70:71], off
	v_lshl_add_u64 v[74:75], s[16:17], 0, v[74:75]
	global_load_dwordx4 v[74:77], v[74:75], off
	v_add_u32_e32 v51, v109, v126
	v_add_u32_e32 v53, v110, v126
	v_add_u32_e32 v78, v109, v128
	v_add_u32_e32 v79, v110, v128
	v_add_u32_e32 v80, v109, v130
	s_and_b32 s27, s28, 0xe00
	v_or_b32_e32 v40, s27, v106
	s_ashr_i32 s27, s26, 31
	s_lshl_b64 s[26:27], s[26:27], 12
	s_waitcnt vmcnt(15)
	ds_write_b128 v134, v[0:3]
	s_waitcnt vmcnt(14)
	ds_write_b128 v135, v[4:7]
	s_waitcnt vmcnt(13)
	ds_write_b128 v51, v[8:11]
	s_waitcnt vmcnt(12)
	ds_write_b128 v53, v[12:15]
	s_waitcnt vmcnt(11)
	ds_write_b128 v134, v[16:19] offset:17408
	s_waitcnt vmcnt(10)
	ds_write_b128 v135, v[20:23] offset:17408
	s_waitcnt vmcnt(9)
	ds_write_b128 v78, v[24:27]
	s_waitcnt vmcnt(8)
	ds_write_b128 v79, v[28:31]
	s_waitcnt vmcnt(7)
	ds_write_b128 v134, v[32:35] offset:34816
	s_waitcnt vmcnt(6)
	ds_write_b128 v135, v[36:39] offset:34816
	s_waitcnt vmcnt(5)
	ds_write_b128 v80, v[54:57]
	v_add_u32_e32 v0, v110, v130
	s_waitcnt vmcnt(4)
	ds_write_b128 v0, v[58:61]
	s_waitcnt vmcnt(3)
	ds_write_b128 v134, v[62:65] offset:52224
	s_waitcnt vmcnt(2)
	ds_write_b128 v135, v[66:69] offset:52224
	v_add_u32_e32 v0, v109, v132
	s_waitcnt vmcnt(1)
	ds_write_b128 v0, v[70:73]
	v_add_u32_e32 v0, v110, v132
	v_and_b32_e32 v1, 64, v137
	s_waitcnt vmcnt(0)
	ds_write_b128 v0, v[74:77]
	v_xor_b32_e32 v0, 16, v137
	v_add_u32_e32 v1, 64, v1
	v_cmp_lt_i32_e32 vcc, v0, v1
	s_waitcnt lgkmcnt(0)
	s_barrier
	v_cndmask_b32_e32 v0, v137, v0, vcc
	v_lshlrev_b32_e32 v51, 2, v0
	v_xor_b32_e32 v0, 32, v137
	v_cmp_lt_i32_e32 vcc, v0, v1
	s_nop 1
	v_cndmask_b32_e32 v0, v137, v0, vcc
	v_lshlrev_b32_e32 v53, 2, v0
	v_lshl_add_u64 v[0:1], v[44:45], 0, s[26:27]
	v_lshl_add_u64 v[0:1], v[0:1], 0, v[40:41]
	v_lshlrev_b64 v[2:3], 2, v[0:1]
	v_lshlrev_b64 v[0:1], 10, v[0:1]
	v_mad_u64_u32 v[16:17], s[26:27], s33, v138, v[2:3]
	v_lshl_add_u64 v[2:3], v[46:47], 0, v[0:1]
	v_lshl_add_u64 v[0:1], v[48:49], 0, v[0:1]
	v_lshl_add_u64 v[18:19], v[2:3], 0, s[2:3]
	v_lshl_add_u64 v[20:21], v[0:1], 0, s[2:3]
	s_mov_b32 s2, 4
	v_readfirstlane_b32 s98, v202
	s_nop 3
	s_cmpk_lt_u32 s98, 0x100
	s_cbranch_scc1 .Lmq_stag_skip
	s_sleep 40
.Lmq_stag_skip:
.LBB0_1059:
	v_lshl_add_u64 v[34:35], s[22:23], 0, v[20:21]
	global_load_dwordx4 v[4:7], v[34:35], off offset:-128 nt
	global_load_dwordx4 v[0:3], v[34:35], off offset:-64 nt
	ds_read_b128 v[12:15], v123
	ds_read_b128 v[22:25], v123 offset:64
	ds_read_b128 v[26:29], v123 offset:4352
	global_load_dwordx4 v[8:11], v[34:35], off nt
	v_lshl_add_u64 v[36:37], s[22:23], 0, v[16:17]
	v_add_co_u32_e32 v38, vcc, 0x18fc4000, v36
	s_waitcnt vmcnt(2) lgkmcnt(2)
	v_mfma_f32_16x16x32_bf16 v[30:33], v[12:15], v[4:7], 0
	v_addc_co_u32_e32 v39, vcc, 0, v37, vcc
	v_add_co_u32_e32 v36, vcc, 0x18fe5000, v36
	s_waitcnt vmcnt(1) lgkmcnt(1)
	v_mfma_f32_16x16x32_bf16 v[22:25], v[22:25], v[0:3], v[30:33]
	v_addc_co_u32_e32 v37, vcc, 0, v37, vcc
	global_load_dword v38, v[38:39], off
	s_nop 0
	global_load_dword v39, v[36:37], off
	global_load_dwordx4 v[12:15], v[34:35], off offset:64 nt
	ds_read_b128 v[30:33], v123 offset:4416
	s_waitcnt lgkmcnt(1)
	v_mfma_f32_16x16x32_bf16 v[26:29], v[26:29], v[4:7], 0
	s_waitcnt vmcnt(1)
	v_add_f32_e32 v38, v38, v39
	s_waitcnt lgkmcnt(0)
	v_mfma_f32_16x16x32_bf16 v[26:29], v[30:33], v[0:3], v[26:29]
	ds_read_b128 v[30:33], v123 offset:128
	ds_read_b128 v[34:37], v123 offset:192
	v_fmamk_f32 v38, v38, 0x3c000000, v136
	s_waitcnt lgkmcnt(1)
	v_mfma_f32_16x16x32_bf16 v[22:25], v[30:33], v[8:11], v[22:25]
	ds_read_b128 v[30:33], v123 offset:4480
	s_waitcnt lgkmcnt(0)
	v_mfma_f32_16x16x32_bf16 v[26:29], v[30:33], v[8:11], v[26:29]
	ds_read_b128 v[30:33], v123 offset:4544
	s_waitcnt vmcnt(0)
	v_mfma_f32_16x16x32_bf16 v[22:25], v[34:37], v[12:15], v[22:25]
	v_rsq_f32_e32 v34, v38
	s_nop 0
	v_mul_f32_e32 v40, 0x3e0293ee, v34
	s_waitcnt lgkmcnt(0)
	v_mfma_f32_16x16x32_bf16 v[30:33], v[30:33], v[12:15], v[26:29]
	s_nop 2
	v_mul_f32_e64 v36, v40, v22
	v_mul_f32_e64 v37, v40, v23
	v_pk_mul_f32 v[28:29], v[40:41], v[24:25] op_sel_hi:[0,1]
	s_nop 1
	v_pk_mul_f32 v[22:23], v[40:41], v[32:33] op_sel_hi:[0,1]
	v_pk_mul_f32 v[26:27], v[40:41], v[30:31] op_sel_hi:[0,1]
	ds_read_b128 v[30:33], v123 offset:8704
	ds_read_b128 v[54:57], v123 offset:8768
	ds_read_b128 v[62:65], v123 offset:8832
	ds_read_b128 v[58:61], v123 offset:13056
	s_waitcnt lgkmcnt(3)
	v_mfma_f32_16x16x32_bf16 v[30:33], v[30:33], v[4:7], 0
	s_waitcnt lgkmcnt(2)
	v_mfma_f32_16x16x32_bf16 v[30:33], v[54:57], v[0:3], v[30:33]
	ds_read_b128 v[54:57], v123 offset:8896
	s_waitcnt lgkmcnt(2)
	v_mfma_f32_16x16x32_bf16 v[30:33], v[62:65], v[8:11], v[30:33]
	s_waitcnt lgkmcnt(0)
	v_mfma_f32_16x16x32_bf16 v[30:33], v[54:57], v[12:15], v[30:33]
	ds_read_b128 v[54:57], v123 offset:13120
	v_mfma_f32_16x16x32_bf16 v[58:61], v[58:61], v[4:7], 0
	s_nop 5
	v_mul_f32_e64 v34, v40, v32
	v_mul_f32_e64 v35, v40, v33
	s_waitcnt lgkmcnt(0)
	v_mfma_f32_16x16x32_bf16 v[54:57], v[54:57], v[0:3], v[58:61]
	s_nop 2
	ds_read_b128 v[58:61], v123 offset:13184
	s_waitcnt lgkmcnt(0)
	v_mfma_f32_16x16x32_bf16 v[54:57], v[58:61], v[8:11], v[54:57]
	ds_read_b128 v[60:63], v123 offset:13248
	v_pk_mul_f32 v[58:59], v[40:41], v[30:31] op_sel_hi:[0,1]
	s_waitcnt lgkmcnt(0)
	v_mfma_f32_16x16x32_bf16 v[30:33], v[60:63], v[12:15], v[54:57]
	s_nop 7
	v_pk_mul_f32 v[24:25], v[40:41], v[32:33] op_sel_hi:[0,1]
	v_pk_mul_f32 v[32:33], v[40:41], v[30:31] op_sel_hi:[0,1]
	ds_read_b128 v[54:57], v123 offset:17408
	ds_read_b128 v[60:63], v123 offset:17472
	ds_read_b128 v[68:71], v123 offset:17536
	ds_read_b128 v[64:67], v123 offset:21760
	s_waitcnt lgkmcnt(3)
	v_mfma_f32_16x16x32_bf16 v[54:57], v[54:57], v[4:7], 0
	s_waitcnt lgkmcnt(2)
	v_mfma_f32_16x16x32_bf16 v[54:57], v[60:63], v[0:3], v[54:57]
	ds_read_b128 v[60:63], v123 offset:17600
	s_waitcnt lgkmcnt(2)
	v_mfma_f32_16x16x32_bf16 v[54:57], v[68:71], v[8:11], v[54:57]
	ds_read_b128 v[68:71], v123 offset:21952
	s_waitcnt lgkmcnt(1)
	v_mfma_f32_16x16x32_bf16 v[54:57], v[60:63], v[12:15], v[54:57]
	ds_read_b128 v[60:63], v123 offset:21824
	v_mfma_f32_16x16x32_bf16 v[64:67], v[64:67], v[4:7], 0
	s_nop 5
	v_mul_f32_e64 v56, v40, v56
	v_mul_f32_e64 v57, v40, v57
	s_waitcnt lgkmcnt(0)
	v_mfma_f32_16x16x32_bf16 v[60:63], v[60:63], v[0:3], v[64:67]
	s_nop 2
	ds_read_b128 v[64:67], v123 offset:21888
	s_waitcnt lgkmcnt(0)
	v_mfma_f32_16x16x32_bf16 v[64:67], v[64:67], v[8:11], v[60:63]
	s_nop 2
	v_mul_f32_e64 v62, v40, v54
	v_mul_f32_e64 v63, v40, v55
	v_mfma_f32_16x16x32_bf16 v[64:67], v[68:71], v[12:15], v[64:67]
	s_nop 7
	v_pk_mul_f32 v[30:31], v[40:41], v[66:67] op_sel_hi:[0,1]
	v_pk_mul_f32 v[54:55], v[40:41], v[64:65] op_sel_hi:[0,1]
	ds_read_b128 v[64:67], v123 offset:26112
	ds_read_b128 v[68:71], v123 offset:26176
	ds_read_b128 v[76:79], v123 offset:26240
	ds_read_b128 v[72:75], v123 offset:30464
	s_waitcnt lgkmcnt(3)
	v_mfma_f32_16x16x32_bf16 v[64:67], v[64:67], v[4:7], 0
	s_waitcnt lgkmcnt(2)
	v_mfma_f32_16x16x32_bf16 v[64:67], v[68:71], v[0:3], v[64:67]
	ds_read_b128 v[68:71], v123 offset:26304
	s_waitcnt lgkmcnt(2)
	v_mfma_f32_16x16x32_bf16 v[64:67], v[76:79], v[8:11], v[64:67]
	ds_read_b128 v[76:79], v123 offset:30656
	s_waitcnt lgkmcnt(1)
	v_mfma_f32_16x16x32_bf16 v[64:67], v[68:71], v[12:15], v[64:67]
	ds_read_b128 v[68:71], v123 offset:30528
	v_mfma_f32_16x16x32_bf16 v[72:75], v[72:75], v[4:7], 0
	s_nop 5
	v_mul_f32_e64 v86, v40, v64
	v_mul_f32_e64 v87, v40, v65
	s_waitcnt lgkmcnt(0)
	v_mfma_f32_16x16x32_bf16 v[68:71], v[68:71], v[0:3], v[72:75]
	s_nop 2
	ds_read_b128 v[72:75], v123 offset:30592
	s_waitcnt lgkmcnt(0)
	v_mfma_f32_16x16x32_bf16 v[68:71], v[72:75], v[8:11], v[68:71]
	v_mul_f32_e64 v74, v40, v66
	v_mul_f32_e64 v75, v40, v67
	v_mfma_f32_16x16x32_bf16 v[64:67], v[76:79], v[12:15], v[68:71]
	s_nop 7
	v_pk_mul_f32 v[38:39], v[40:41], v[66:67] op_sel_hi:[0,1]
	v_pk_mul_f32 v[60:61], v[40:41], v[64:65] op_sel_hi:[0,1]
	ds_read_b128 v[64:67], v123 offset:34816
	ds_read_b128 v[68:71], v123 offset:34880
	ds_read_b128 v[80:83], v123 offset:34944
	ds_read_b128 v[76:79], v123 offset:39168
	s_waitcnt lgkmcnt(3)
	v_mfma_f32_16x16x32_bf16 v[64:67], v[64:67], v[4:7], 0
	s_waitcnt lgkmcnt(2)
	v_mfma_f32_16x16x32_bf16 v[64:67], v[68:71], v[0:3], v[64:67]
	ds_read_b128 v[68:71], v123 offset:35008
	s_waitcnt lgkmcnt(2)
	v_mfma_f32_16x16x32_bf16 v[64:67], v[80:83], v[8:11], v[64:67]
	s_waitcnt lgkmcnt(0)
	v_mfma_f32_16x16x32_bf16 v[64:67], v[68:71], v[12:15], v[64:67]
	ds_read_b128 v[68:71], v123 offset:39232
	v_mfma_f32_16x16x32_bf16 v[76:79], v[76:79], v[4:7], 0
	s_nop 5
	v_mul_f32_e64 v84, v40, v66
	v_mul_f32_e64 v85, v40, v67
	v_pk_mul_f32 v[94:95], v[40:41], v[64:65] op_sel_hi:[0,1]
	s_waitcnt lgkmcnt(0)
	v_mfma_f32_16x16x32_bf16 v[68:71], v[68:71], v[0:3], v[76:79]
	s_nop 2
	ds_read_b128 v[76:79], v123 offset:39296
	s_waitcnt lgkmcnt(0)
	v_mfma_f32_16x16x32_bf16 v[68:71], v[76:79], v[8:11], v[68:71]
	ds_read_b128 v[76:79], v123 offset:39360
	s_waitcnt lgkmcnt(0)
	v_mfma_f32_16x16x32_bf16 v[64:67], v[76:79], v[12:15], v[68:71]
	s_nop 7
	v_pk_mul_f32 v[72:73], v[40:41], v[66:67] op_sel_hi:[0,1]
	v_pk_mul_f32 v[78:79], v[40:41], v[64:65] op_sel_hi:[0,1]
	ds_read_b128 v[64:67], v123 offset:43520
	ds_read_b128 v[68:71], v123 offset:43584
	ds_read_b128 v[88:91], v123 offset:43648
	ds_read_b128 v[80:83], v123 offset:47872
	s_waitcnt lgkmcnt(3)
	v_mfma_f32_16x16x32_bf16 v[64:67], v[64:67], v[4:7], 0
	s_waitcnt lgkmcnt(2)
	v_mfma_f32_16x16x32_bf16 v[64:67], v[68:71], v[0:3], v[64:67]
	ds_read_b128 v[68:71], v123 offset:43712
	s_waitcnt lgkmcnt(2)
	v_mfma_f32_16x16x32_bf16 v[64:67], v[88:91], v[8:11], v[64:67]
	s_waitcnt lgkmcnt(0)
	v_mfma_f32_16x16x32_bf16 v[64:67], v[68:71], v[12:15], v[64:67]
	ds_read_b128 v[68:71], v123 offset:47936
	v_mfma_f32_16x16x32_bf16 v[80:83], v[80:83], v[4:7], 0
	s_nop 5
	v_mul_f32_e64 v92, v40, v66
	v_mul_f32_e64 v93, v40, v67
	v_pk_mul_f32 v[102:103], v[40:41], v[64:65] op_sel_hi:[0,1]
	s_waitcnt lgkmcnt(0)
	v_mfma_f32_16x16x32_bf16 v[68:71], v[68:71], v[0:3], v[80:83]
	s_nop 2
	ds_read_b128 v[80:83], v123 offset:48000
	s_waitcnt lgkmcnt(0)
	v_mfma_f32_16x16x32_bf16 v[68:71], v[80:83], v[8:11], v[68:71]
	ds_read_b128 v[80:83], v123 offset:48064
	s_waitcnt lgkmcnt(0)
	v_mfma_f32_16x16x32_bf16 v[64:67], v[80:83], v[12:15], v[68:71]
	s_nop 7
	v_pk_mul_f32 v[76:77], v[40:41], v[66:67] op_sel_hi:[0,1]
	v_pk_mul_f32 v[90:91], v[40:41], v[64:65] op_sel_hi:[0,1]
	ds_read_b128 v[64:67], v123 offset:52224
	ds_read_b128 v[68:71], v123 offset:52288
	ds_read_b128 v[96:99], v123 offset:52352
	ds_read_b128 v[80:83], v123 offset:56576
	s_waitcnt lgkmcnt(3)
	v_mfma_f32_16x16x32_bf16 v[64:67], v[64:67], v[4:7], 0
	s_waitcnt lgkmcnt(2)
	v_mfma_f32_16x16x32_bf16 v[64:67], v[68:71], v[0:3], v[64:67]
	ds_read_b128 v[68:71], v123 offset:52416
	s_waitcnt lgkmcnt(2)
	v_mfma_f32_16x16x32_bf16 v[64:67], v[96:99], v[8:11], v[64:67]
	s_waitcnt lgkmcnt(0)
	v_mfma_f32_16x16x32_bf16 v[64:67], v[68:71], v[12:15], v[64:67]
	ds_read_b128 v[68:71], v123 offset:56640
	v_mfma_f32_16x16x32_bf16 v[80:83], v[80:83], v[4:7], 0
	s_nop 5
	v_mul_f32_e64 v100, v40, v66
	v_mul_f32_e64 v101, v40, v67
	v_pk_mul_f32 v[104:105], v[40:41], v[64:65] op_sel_hi:[0,1]
	s_waitcnt lgkmcnt(0)
	v_mfma_f32_16x16x32_bf16 v[68:71], v[68:71], v[0:3], v[80:83]
	s_nop 2
	ds_read_b128 v[80:83], v123 offset:56704
	s_waitcnt lgkmcnt(0)
	v_mfma_f32_16x16x32_bf16 v[68:71], v[80:83], v[8:11], v[68:71]
	ds_read_b128 v[80:83], v123 offset:56768
	s_waitcnt lgkmcnt(0)
	v_mfma_f32_16x16x32_bf16 v[64:67], v[80:83], v[12:15], v[68:71]
	s_nop 7
	v_pk_mul_f32 v[88:89], v[40:41], v[66:67] op_sel_hi:[0,1]
	v_pk_mul_f32 v[98:99], v[40:41], v[64:65] op_sel_hi:[0,1]
	ds_read_b128 v[64:67], v123 offset:60928
	ds_read_b128 v[68:71], v123 offset:60992
	ds_read_b128 v[80:83], v123 offset:65280
	s_waitcnt lgkmcnt(2)
	v_mfma_f32_16x16x32_bf16 v[64:67], v[64:67], v[4:7], 0
	s_waitcnt lgkmcnt(1)
	v_mfma_f32_16x16x32_bf16 v[64:67], v[68:71], v[0:3], v[64:67]
	ds_read_b128 v[68:71], v123 offset:61120
	s_waitcnt lgkmcnt(1)
	v_mfma_f32_16x16x32_bf16 v[4:7], v[80:83], v[4:7], 0
	ds_read_b128 v[80:83], v123 offset:61056
	s_waitcnt lgkmcnt(0)
	v_mfma_f32_16x16x32_bf16 v[64:67], v[80:83], v[8:11], v[64:67]
	v_mfma_f32_16x16x32_bf16 v[64:67], v[68:71], v[12:15], v[64:67]
	ds_read_b128 v[68:71], v123 offset:65344
	s_waitcnt lgkmcnt(0)
	v_mfma_f32_16x16x32_bf16 v[0:3], v[68:71], v[0:3], v[4:7]
	s_nop 2
	ds_read_b128 v[4:7], v123 offset:65408
	ds_read_b128 v[68:71], v123 offset:65472
	s_waitcnt lgkmcnt(1)
	v_mfma_f32_16x16x32_bf16 v[6:9], v[4:7], v[8:11], v[0:3]
	v_mul_f32_e64 v4, v40, v66
	v_mul_f32_e64 v5, v40, v67
	s_nop 0
	v_pk_mul_f32 v[0:1], v[40:41], v[64:65] op_sel_hi:[0,1]
	s_waitcnt lgkmcnt(0)
	v_mfma_f32_16x16x32_bf16 v[8:11], v[68:71], v[12:15], v[6:9]
	s_nop 7
	v_pk_mul_f32 v[6:7], v[40:41], v[10:11] op_sel_hi:[0,1]
	v_pk_mul_f32 v[2:3], v[40:41], v[8:9] op_sel_hi:[0,1]
	v_max_f32_e32 v8, v36, v37
	v_max_f32_e32 v9, v28, v29
	v_max3_f32 v8, v8, s30, v9
	v_max_f32_e32 v9, v26, v27
	v_max_f32_e32 v10, v22, v23
	v_max3_f32 v8, v8, v9, v10
	v_max_f32_e32 v9, v58, v59
	v_max_f32_e32 v10, v34, v35
	v_max3_f32 v8, v8, v9, v10
	v_max_f32_e32 v9, v32, v33
	v_max_f32_e32 v10, v24, v25
	v_max3_f32 v8, v8, v9, v10
	v_max_f32_e32 v9, v62, v63
	v_max_f32_e32 v10, v56, v57
	v_max3_f32 v8, v8, v9, v10
	v_max_f32_e32 v9, v54, v55
	v_max_f32_e32 v10, v30, v31
	v_max3_f32 v8, v8, v9, v10
	v_max_f32_e32 v9, v86, v87
	v_max_f32_e32 v10, v74, v75
	v_max3_f32 v8, v8, v9, v10
	v_max_f32_e32 v9, v60, v61
	v_max_f32_e32 v10, v38, v39
	v_max3_f32 v8, v8, v9, v10
	v_max_f32_e32 v9, v94, v95
	v_max_f32_e32 v10, v84, v85
	v_max3_f32 v8, v8, v9, v10
	v_max_f32_e32 v9, v78, v79
	v_max_f32_e32 v10, v72, v73
	v_max3_f32 v8, v8, v9, v10
	v_max_f32_e32 v9, v102, v103
	v_max_f32_e32 v10, v92, v93
	v_max3_f32 v8, v8, v9, v10
	v_max_f32_e32 v9, v90, v91
	v_max_f32_e32 v10, v76, v77
	v_max3_f32 v8, v8, v9, v10
	v_max_f32_e32 v9, v104, v105
	v_max_f32_e32 v10, v100, v101
	v_max3_f32 v8, v8, v9, v10
	v_max_f32_e32 v9, v98, v99
	v_max_f32_e32 v10, v88, v89
	v_max3_f32 v8, v8, v9, v10
	v_max_f32_e32 v9, v0, v1
	v_max_f32_e32 v10, v4, v5
	v_max3_f32 v8, v8, v9, v10
	v_max_f32_e32 v9, v2, v3
	v_max_f32_e32 v10, v6, v7
	v_max3_f32 v8, v8, v9, v10
	ds_bpermute_b32 v9, v51, v8
	s_waitcnt lgkmcnt(0)
	v_max_f32_e32 v9, v9, v9
	v_max_f32_e32 v8, v8, v9
	ds_bpermute_b32 v9, v53, v8
	s_waitcnt lgkmcnt(0)
	v_max_f32_e32 v9, v9, v9
	v_max_f32_e32 v8, v8, v9
	v_sub_f32_e32 v9, v36, v8
	v_exp_f32_e32 v140, v9
	v_sub_f32_e32 v9, v37, v8
	v_exp_f32_e32 v141, v9
	v_sub_f32_e32 v9, v28, v8
	v_exp_f32_e32 v142, v9
	v_sub_f32_e32 v9, v29, v8
	v_exp_f32_e32 v143, v9
	v_sub_f32_e32 v10, v26, v8
	v_add_f32_e32 v9, 0, v140
	v_exp_f32_e32 v144, v10
	v_sub_f32_e32 v10, v27, v8
	v_add_f32_e32 v9, v141, v9
	v_exp_f32_e32 v145, v10
	v_sub_f32_e32 v10, v22, v8
	v_add_f32_e32 v9, v142, v9
	v_exp_f32_e32 v146, v10
	v_sub_f32_e32 v10, v23, v8
	v_add_f32_e32 v9, v143, v9
	v_exp_f32_e32 v147, v10
	v_sub_f32_e32 v10, v58, v8
	v_add_f32_e32 v9, v144, v9
	v_exp_f32_e32 v70, v10
	v_sub_f32_e32 v10, v59, v8
	v_add_f32_e32 v9, v145, v9
	v_exp_f32_e32 v71, v10
	v_sub_f32_e32 v10, v34, v8
	v_add_f32_e32 v9, v146, v9
	v_exp_f32_e32 v82, v10
	v_sub_f32_e32 v10, v35, v8
	v_add_f32_e32 v9, v147, v9
	v_exp_f32_e32 v83, v10
	v_sub_f32_e32 v10, v32, v8
	v_add_f32_e32 v9, v70, v9
	v_exp_f32_e32 v80, v10
	v_sub_f32_e32 v10, v33, v8
	v_add_f32_e32 v9, v71, v9
	v_exp_f32_e32 v81, v10
	v_sub_f32_e32 v10, v24, v8
	v_add_f32_e32 v9, v82, v9
	v_exp_f32_e32 v96, v10
	v_sub_f32_e32 v10, v25, v8
	v_add_f32_e32 v9, v83, v9
	v_exp_f32_e32 v97, v10
	v_sub_f32_e32 v10, v62, v8
	v_add_f32_e32 v9, v80, v9
	v_exp_f32_e32 v62, v10
	v_sub_f32_e32 v10, v63, v8
	v_add_f32_e32 v9, v81, v9
	v_exp_f32_e32 v63, v10
	v_sub_f32_e32 v10, v56, v8
	v_add_f32_e32 v9, v96, v9
	v_exp_f32_e32 v66, v10
	v_sub_f32_e32 v10, v57, v8
	v_add_f32_e32 v9, v97, v9
	v_exp_f32_e32 v67, v10
	v_sub_f32_e32 v10, v54, v8
	v_add_f32_e32 v9, v62, v9
	v_exp_f32_e32 v64, v10
	v_sub_f32_e32 v10, v55, v8
	v_add_f32_e32 v9, v63, v9
	v_exp_f32_e32 v65, v10
	v_sub_f32_e32 v10, v30, v8
	v_add_f32_e32 v9, v66, v9
	v_exp_f32_e32 v68, v10
	v_sub_f32_e32 v10, v31, v8
	v_add_f32_e32 v9, v67, v9
	v_exp_f32_e32 v69, v10
	v_sub_f32_e32 v10, v86, v8
	v_add_f32_e32 v9, v64, v9
	v_exp_f32_e32 v54, v10
	v_sub_f32_e32 v10, v87, v8
	v_add_f32_e32 v9, v65, v9
	v_exp_f32_e32 v55, v10
	v_sub_f32_e32 v10, v74, v8
	v_add_f32_e32 v9, v68, v9
	v_exp_f32_e32 v58, v10
	v_sub_f32_e32 v10, v75, v8
	v_add_f32_e32 v9, v69, v9
	v_exp_f32_e32 v59, v10
	v_sub_f32_e32 v10, v60, v8
	v_add_f32_e32 v9, v54, v9
	v_exp_f32_e32 v56, v10
	v_sub_f32_e32 v10, v61, v8
	v_add_f32_e32 v9, v55, v9
	v_exp_f32_e32 v57, v10
	v_sub_f32_e32 v10, v38, v8
	v_add_f32_e32 v9, v58, v9
	v_exp_f32_e32 v60, v10
	v_sub_f32_e32 v10, v39, v8
	v_add_f32_e32 v9, v59, v9
	v_exp_f32_e32 v61, v10
	v_sub_f32_e32 v10, v94, v8
	v_add_f32_e32 v9, v56, v9
	v_exp_f32_e32 v32, v10
	v_sub_f32_e32 v10, v95, v8
	v_add_f32_e32 v9, v57, v9
	v_exp_f32_e32 v33, v10
	v_sub_f32_e32 v10, v84, v8
	v_add_f32_e32 v9, v60, v9
	v_exp_f32_e32 v36, v10
	v_sub_f32_e32 v10, v85, v8
	v_add_f32_e32 v9, v61, v9
	v_exp_f32_e32 v37, v10
	v_sub_f32_e32 v10, v78, v8
	v_add_f32_e32 v9, v32, v9
	v_exp_f32_e32 v34, v10
	v_sub_f32_e32 v10, v79, v8
	v_add_f32_e32 v9, v33, v9
	v_exp_f32_e32 v35, v10
	v_sub_f32_e32 v10, v72, v8
	v_add_f32_e32 v9, v36, v9
	v_exp_f32_e32 v38, v10
	v_sub_f32_e32 v10, v73, v8
	v_add_f32_e32 v9, v37, v9
	v_exp_f32_e32 v39, v10
	v_sub_f32_e32 v10, v102, v8
	v_add_f32_e32 v9, v34, v9
	v_exp_f32_e32 v24, v10
	v_sub_f32_e32 v10, v103, v8
	v_add_f32_e32 v9, v35, v9
	v_exp_f32_e32 v25, v10
	v_sub_f32_e32 v10, v92, v8
	v_add_f32_e32 v9, v38, v9
	v_exp_f32_e32 v28, v10
	v_sub_f32_e32 v10, v93, v8
	v_add_f32_e32 v9, v39, v9
	v_exp_f32_e32 v29, v10
	v_sub_f32_e32 v10, v90, v8
	v_add_f32_e32 v9, v24, v9
	v_exp_f32_e32 v26, v10
	v_sub_f32_e32 v10, v91, v8
	v_add_f32_e32 v9, v25, v9
	v_exp_f32_e32 v27, v10
	v_sub_f32_e32 v10, v76, v8
	v_add_f32_e32 v9, v28, v9
	v_exp_f32_e32 v30, v10
	v_sub_f32_e32 v10, v77, v8
	v_add_f32_e32 v9, v29, v9
	v_exp_f32_e32 v31, v10
	v_sub_f32_e32 v10, v104, v8
	v_add_f32_e32 v9, v26, v9
	v_exp_f32_e32 v10, v10
	v_sub_f32_e32 v11, v105, v8
	v_add_f32_e32 v9, v27, v9
	v_exp_f32_e32 v11, v11
	v_sub_f32_e32 v12, v100, v8
	v_add_f32_e32 v9, v30, v9
	v_exp_f32_e32 v14, v12
	v_sub_f32_e32 v12, v101, v8
	v_add_f32_e32 v9, v31, v9
	v_exp_f32_e32 v15, v12
	v_sub_f32_e32 v12, v98, v8
	v_add_f32_e32 v9, v10, v9
	v_exp_f32_e32 v12, v12
	v_sub_f32_e32 v13, v99, v8
	v_add_f32_e32 v9, v11, v9
	v_exp_f32_e32 v13, v13
	v_sub_f32_e32 v22, v88, v8
	v_add_f32_e32 v9, v14, v9
	v_exp_f32_e32 v22, v22
	v_sub_f32_e32 v23, v89, v8
	v_add_f32_e32 v9, v15, v9
	v_exp_f32_e32 v23, v23
	v_sub_f32_e32 v0, v0, v8
	v_add_f32_e32 v9, v12, v9
	v_exp_f32_e32 v0, v0
	v_sub_f32_e32 v1, v1, v8
	v_add_f32_e32 v9, v13, v9
	v_exp_f32_e32 v1, v1
	v_sub_f32_e32 v4, v4, v8
	v_add_f32_e32 v9, v22, v9
	v_exp_f32_e32 v4, v4
	v_sub_f32_e32 v5, v5, v8
	v_add_f32_e32 v9, v23, v9
	v_exp_f32_e32 v5, v5
	v_sub_f32_e32 v2, v2, v8
	v_add_f32_e32 v9, v0, v9
	v_exp_f32_e32 v2, v2
	v_sub_f32_e32 v3, v3, v8
	v_add_f32_e32 v9, v1, v9
	v_exp_f32_e32 v3, v3
	v_sub_f32_e32 v6, v6, v8
	v_add_f32_e32 v9, v4, v9
	v_exp_f32_e32 v6, v6
	v_sub_f32_e32 v7, v7, v8
	v_add_f32_e32 v9, v5, v9
	v_exp_f32_e32 v7, v7
	v_add_f32_e32 v8, v2, v9
	v_add_f32_e32 v8, v3, v8
	v_add_f32_e32 v8, v6, v8
	v_add_f32_e32 v8, v7, v8
	ds_bpermute_b32 v9, v51, v8
	ds_read_b64_tr_b16 v[78:79], v133 offset:4352
	ds_read_b64_tr_b16 v[76:77], v133
	s_waitcnt lgkmcnt(2)
	v_add_f32_e32 v8, v8, v9
	ds_bpermute_b32 v9, v53, v8
	s_waitcnt lgkmcnt(0)
	v_add_f32_e32 v8, v8, v9
	v_rcp_f32_e32 v8, v8
	s_nop 0
	v_pk_mul_f32 v[74:75], v[142:143], v[8:9] op_sel_hi:[1,0]
	v_pk_mul_f32 v[72:73], v[140:141], v[8:9] op_sel_hi:[1,0]
	v_pk_mul_f32 v[84:85], v[146:147], v[8:9] op_sel_hi:[1,0]
	v_pk_mul_f32 v[86:87], v[144:145], v[8:9] op_sel_hi:[1,0]
	v_cvt_pk_bf16_f32 v72, v72, v73
	v_cvt_pk_bf16_f32 v73, v74, v75
	v_cvt_pk_bf16_f32 v74, v86, v87
	v_cvt_pk_bf16_f32 v75, v84, v85
	ds_read_b64_tr_b16 v[86:87], v133 offset:4384
	ds_read_b64_tr_b16 v[84:85], v133 offset:32
	ds_read_b64_tr_b16 v[88:89], v133 offset:64
	ds_read_b64_tr_b16 v[92:93], v133 offset:96
	ds_read_b64_tr_b16 v[90:91], v133 offset:4416
	ds_read_b64_tr_b16 v[94:95], v133 offset:4448
	ds_read_b64_tr_b16 v[98:99], v133 offset:128
	ds_read_b64_tr_b16 v[100:101], v133 offset:4480
	ds_read_b64_tr_b16 v[104:105], v133 offset:4512
	ds_read_b64_tr_b16 v[102:103], v133 offset:160
	ds_read_b64_tr_b16 v[140:141], v133 offset:192
	ds_read_b64_tr_b16 v[144:145], v133 offset:224
	ds_read_b64_tr_b16 v[142:143], v133 offset:4544
	ds_read_b64_tr_b16 v[146:147], v133 offset:4576
	v_mfma_f32_16x16x32_bf16 v[76:79], v[76:79], v[72:75], 0
	s_waitcnt lgkmcnt(12)
	v_mfma_f32_16x16x32_bf16 v[84:87], v[84:87], v[72:75], 0
	s_waitcnt lgkmcnt(9)
	v_mfma_f32_16x16x32_bf16 v[88:91], v[88:91], v[72:75], 0
	s_waitcnt lgkmcnt(8)
	v_mfma_f32_16x16x32_bf16 v[92:95], v[92:95], v[72:75], 0
	s_waitcnt lgkmcnt(6)
	v_mfma_f32_16x16x32_bf16 v[98:101], v[98:101], v[72:75], 0
	s_waitcnt lgkmcnt(4)
	v_mfma_f32_16x16x32_bf16 v[102:105], v[102:105], v[72:75], 0
	s_waitcnt lgkmcnt(1)
	v_mfma_f32_16x16x32_bf16 v[140:143], v[140:143], v[72:75], 0
	s_waitcnt lgkmcnt(0)
	v_mfma_f32_16x16x32_bf16 v[72:75], v[144:147], v[72:75], 0
	v_mul_f32_e64 v82, v82, v8
	v_mul_f32_e64 v83, v83, v8
	v_pk_mul_f32 v[148:149], v[80:81], v[8:9] op_sel_hi:[1,0]
	v_cvt_pk_bf16_f32 v81, v82, v83
	ds_read_b64_tr_b16 v[146:147], v133 offset:13056
	ds_read_b64_tr_b16 v[144:145], v133 offset:8704
	v_cvt_pk_bf16_f32 v82, v148, v149
	ds_read_b64_tr_b16 v[150:151], v133 offset:13088
	ds_read_b64_tr_b16 v[148:149], v133 offset:8736
	ds_read_b64_tr_b16 v[152:153], v133 offset:8768
	ds_read_b64_tr_b16 v[156:157], v133 offset:8800
	ds_read_b64_tr_b16 v[154:155], v133 offset:13120
	ds_read_b64_tr_b16 v[158:159], v133 offset:13152
	v_pk_mul_f32 v[70:71], v[70:71], v[8:9] op_sel_hi:[1,0]
	v_pk_mul_f32 v[96:97], v[96:97], v[8:9] op_sel_hi:[1,0]
	v_cvt_pk_bf16_f32 v80, v70, v71
	v_cvt_pk_bf16_f32 v83, v96, v97
	s_waitcnt lgkmcnt(6)
	s_nop 0
	v_mfma_f32_16x16x32_bf16 v[76:79], v[144:147], v[80:83], v[76:79]
	ds_read_b64_tr_b16 v[144:145], v133 offset:8832
	ds_read_b64_tr_b16 v[146:147], v133 offset:13184
	s_waitcnt lgkmcnt(6)
	v_mfma_f32_16x16x32_bf16 v[84:87], v[148:151], v[80:83], v[84:87]
	s_waitcnt lgkmcnt(3)
	v_mfma_f32_16x16x32_bf16 v[88:91], v[152:155], v[80:83], v[88:91]
	s_waitcnt lgkmcnt(2)
	v_mfma_f32_16x16x32_bf16 v[92:95], v[156:159], v[80:83], v[92:95]
	ds_read_b64_tr_b16 v[150:151], v133 offset:13216
	ds_read_b64_tr_b16 v[148:149], v133 offset:8864
	ds_read_b64_tr_b16 v[152:153], v133 offset:8896
	ds_read_b64_tr_b16 v[156:157], v133 offset:8928
	ds_read_b64_tr_b16 v[154:155], v133 offset:13248
	ds_read_b64_tr_b16 v[158:159], v133 offset:13280
	s_waitcnt lgkmcnt(6)
	v_mfma_f32_16x16x32_bf16 v[96:99], v[144:147], v[80:83], v[98:101]
	s_waitcnt lgkmcnt(4)
	v_mfma_f32_16x16x32_bf16 v[100:103], v[148:151], v[80:83], v[102:105]
	s_waitcnt lgkmcnt(1)
	v_mfma_f32_16x16x32_bf16 v[140:143], v[152:155], v[80:83], v[140:143]
	s_waitcnt lgkmcnt(0)
	v_mfma_f32_16x16x32_bf16 v[70:73], v[156:159], v[80:83], v[72:75]
	v_mul_f32_e64 v66, v66, v8
	v_mul_f32_e64 v67, v67, v8
	v_pk_mul_f32 v[62:63], v[62:63], v[8:9] op_sel_hi:[1,0]
	v_pk_mul_f32 v[74:75], v[68:69], v[8:9] op_sel_hi:[1,0]
	v_cvt_pk_bf16_f32 v62, v62, v63
	v_cvt_pk_bf16_f32 v63, v66, v67
	ds_read_b64_tr_b16 v[68:69], v133 offset:21760
	ds_read_b64_tr_b16 v[66:67], v133 offset:17408
	ds_read_b64_tr_b16 v[82:83], v133 offset:21792
	ds_read_b64_tr_b16 v[80:81], v133 offset:17440
	ds_read_b64_tr_b16 v[144:145], v133 offset:17472
	ds_read_b64_tr_b16 v[148:149], v133 offset:17504
	ds_read_b64_tr_b16 v[146:147], v133 offset:21824
	ds_read_b64_tr_b16 v[150:151], v133 offset:21856
	v_pk_mul_f32 v[64:65], v[64:65], v[8:9] op_sel_hi:[1,0]
	s_nop 0
	v_cvt_pk_bf16_f32 v64, v64, v65
	v_cvt_pk_bf16_f32 v65, v74, v75
	s_waitcnt lgkmcnt(6)
	s_nop 0
	v_mfma_f32_16x16x32_bf16 v[66:69], v[66:69], v[62:65], v[76:79]
	s_waitcnt lgkmcnt(4)
	v_mfma_f32_16x16x32_bf16 v[74:77], v[80:83], v[62:65], v[84:87]
	ds_read_b64_tr_b16 v[82:83], v133 offset:17536
	s_nop 1
	ds_read_b64_tr_b16 v[84:85], v133 offset:21888
	s_waitcnt lgkmcnt(3)
	v_mfma_f32_16x16x32_bf16 v[78:81], v[144:147], v[62:65], v[88:91]
	s_waitcnt lgkmcnt(2)
	v_mfma_f32_16x16x32_bf16 v[86:89], v[148:151], v[62:65], v[92:95]
	s_nop 2
	ds_read_b64_tr_b16 v[92:93], v133 offset:21920
	ds_read_b64_tr_b16 v[90:91], v133 offset:17568
	ds_read_b64_tr_b16 v[144:145], v133 offset:17600
	ds_read_b64_tr_b16 v[148:149], v133 offset:17632
	ds_read_b64_tr_b16 v[146:147], v133 offset:21952
	ds_read_b64_tr_b16 v[150:151], v133 offset:21984
	s_waitcnt lgkmcnt(6)
	v_mfma_f32_16x16x32_bf16 v[82:85], v[82:85], v[62:65], v[96:99]
	s_waitcnt lgkmcnt(4)
	v_mfma_f32_16x16x32_bf16 v[90:93], v[90:93], v[62:65], v[100:103]
	s_waitcnt lgkmcnt(1)
	v_mfma_f32_16x16x32_bf16 v[94:97], v[144:147], v[62:65], v[140:143]
	s_waitcnt lgkmcnt(0)
	v_mfma_f32_16x16x32_bf16 v[62:65], v[148:151], v[62:65], v[70:73]
	v_mul_f32_e64 v58, v58, v8
	v_mul_f32_e64 v59, v59, v8
	v_pk_mul_f32 v[54:55], v[54:55], v[8:9] op_sel_hi:[1,0]
	v_pk_mul_f32 v[70:71], v[60:61], v[8:9] op_sel_hi:[1,0]
	v_pk_mul_f32 v[56:57], v[56:57], v[8:9] op_sel_hi:[1,0]
	v_cvt_pk_bf16_f32 v54, v54, v55
	v_cvt_pk_bf16_f32 v55, v58, v59
	ds_read_b64_tr_b16 v[60:61], v133 offset:30464
	ds_read_b64_tr_b16 v[58:59], v133 offset:26112
	v_cvt_pk_bf16_f32 v56, v56, v57
	v_cvt_pk_bf16_f32 v57, v70, v71
	ds_read_b64_tr_b16 v[72:73], v133 offset:30496
	ds_read_b64_tr_b16 v[70:71], v133 offset:26144
	ds_read_b64_tr_b16 v[98:99], v133 offset:26176
	ds_read_b64_tr_b16 v[102:103], v133 offset:26208
	ds_read_b64_tr_b16 v[100:101], v133 offset:30528
	ds_read_b64_tr_b16 v[104:105], v133 offset:30560
	s_waitcnt lgkmcnt(6)
	v_mfma_f32_16x16x32_bf16 v[58:61], v[58:61], v[54:57], v[66:69]
	s_waitcnt lgkmcnt(4)
	v_mfma_f32_16x16x32_bf16 v[66:69], v[70:73], v[54:57], v[74:77]
	s_nop 2
	ds_read_b64_tr_b16 v[74:75], v133 offset:26240
	ds_read_b64_tr_b16 v[76:77], v133 offset:30592
	s_waitcnt lgkmcnt(3)
	v_mfma_f32_16x16x32_bf16 v[70:73], v[98:101], v[54:57], v[78:81]
	s_waitcnt lgkmcnt(2)
	v_mfma_f32_16x16x32_bf16 v[78:81], v[102:105], v[54:57], v[86:89]
	s_nop 2
	ds_read_b64_tr_b16 v[88:89], v133 offset:30624
	ds_read_b64_tr_b16 v[86:87], v133 offset:26272
	ds_read_b64_tr_b16 v[98:99], v133 offset:26304
	ds_read_b64_tr_b16 v[102:103], v133 offset:26336
	ds_read_b64_tr_b16 v[100:101], v133 offset:30656
	ds_read_b64_tr_b16 v[104:105], v133 offset:30688
	s_waitcnt lgkmcnt(6)
	v_mfma_f32_16x16x32_bf16 v[74:77], v[74:77], v[54:57], v[82:85]
	s_waitcnt lgkmcnt(4)
	v_mfma_f32_16x16x32_bf16 v[82:85], v[86:89], v[54:57], v[90:93]
	s_waitcnt lgkmcnt(1)
	v_mfma_f32_16x16x32_bf16 v[86:89], v[98:101], v[54:57], v[94:97]
	s_waitcnt lgkmcnt(0)
	v_mfma_f32_16x16x32_bf16 v[54:57], v[102:105], v[54:57], v[62:65]
	v_mul_f32_e64 v36, v36, v8
	v_mul_f32_e64 v37, v37, v8
	v_pk_mul_f32 v[32:33], v[32:33], v[8:9] op_sel_hi:[1,0]
	v_pk_mul_f32 v[62:63], v[38:39], v[8:9] op_sel_hi:[1,0]
	v_pk_mul_f32 v[34:35], v[34:35], v[8:9] op_sel_hi:[1,0]
	v_cvt_pk_bf16_f32 v32, v32, v33
	v_cvt_pk_bf16_f32 v33, v36, v37
	ds_read_b64_tr_b16 v[38:39], v133 offset:39168
	ds_read_b64_tr_b16 v[36:37], v133 offset:34816
	v_cvt_pk_bf16_f32 v34, v34, v35
	v_cvt_pk_bf16_f32 v35, v62, v63
	ds_read_b64_tr_b16 v[64:65], v133 offset:39200
	ds_read_b64_tr_b16 v[62:63], v133 offset:34848
	ds_read_b64_tr_b16 v[90:91], v133 offset:34880
	ds_read_b64_tr_b16 v[94:95], v133 offset:34912
	ds_read_b64_tr_b16 v[92:93], v133 offset:39232
	ds_read_b64_tr_b16 v[96:97], v133 offset:39264
	s_waitcnt lgkmcnt(6)
	v_mfma_f32_16x16x32_bf16 v[36:39], v[36:39], v[32:35], v[58:61]
	s_waitcnt lgkmcnt(4)
	v_mfma_f32_16x16x32_bf16 v[58:61], v[62:65], v[32:35], v[66:69]
	s_nop 2
	ds_read_b64_tr_b16 v[66:67], v133 offset:34944
	ds_read_b64_tr_b16 v[68:69], v133 offset:39296
	s_waitcnt lgkmcnt(3)
	v_mfma_f32_16x16x32_bf16 v[62:65], v[90:93], v[32:35], v[70:73]
	s_waitcnt lgkmcnt(2)
	v_mfma_f32_16x16x32_bf16 v[70:73], v[94:97], v[32:35], v[78:81]
	s_nop 2
	ds_read_b64_tr_b16 v[80:81], v133 offset:39328
	ds_read_b64_tr_b16 v[78:79], v133 offset:34976
	ds_read_b64_tr_b16 v[90:91], v133 offset:35008
	ds_read_b64_tr_b16 v[94:95], v133 offset:35040
	ds_read_b64_tr_b16 v[92:93], v133 offset:39360
	ds_read_b64_tr_b16 v[96:97], v133 offset:39392
	s_waitcnt lgkmcnt(6)
	v_mfma_f32_16x16x32_bf16 v[66:69], v[66:69], v[32:35], v[74:77]
	s_waitcnt lgkmcnt(4)
	v_mfma_f32_16x16x32_bf16 v[74:77], v[78:81], v[32:35], v[82:85]
	s_waitcnt lgkmcnt(1)
	v_mfma_f32_16x16x32_bf16 v[78:81], v[90:93], v[32:35], v[86:89]
	s_waitcnt lgkmcnt(0)
	v_mfma_f32_16x16x32_bf16 v[32:35], v[94:97], v[32:35], v[54:57]
	v_mul_f32_e64 v28, v28, v8
	v_mul_f32_e64 v29, v29, v8
	v_pk_mul_f32 v[24:25], v[24:25], v[8:9] op_sel_hi:[1,0]
	v_pk_mul_f32 v[54:55], v[30:31], v[8:9] op_sel_hi:[1,0]
	v_pk_mul_f32 v[26:27], v[26:27], v[8:9] op_sel_hi:[1,0]
	v_cvt_pk_bf16_f32 v24, v24, v25
	v_cvt_pk_bf16_f32 v25, v28, v29
	ds_read_b64_tr_b16 v[30:31], v133 offset:47872
	ds_read_b64_tr_b16 v[28:29], v133 offset:43520
	v_cvt_pk_bf16_f32 v26, v26, v27
	v_cvt_pk_bf16_f32 v27, v54, v55
	ds_read_b64_tr_b16 v[56:57], v133 offset:47904
	ds_read_b64_tr_b16 v[54:55], v133 offset:43552
	ds_read_b64_tr_b16 v[82:83], v133 offset:43584
	ds_read_b64_tr_b16 v[86:87], v133 offset:43616
	ds_read_b64_tr_b16 v[84:85], v133 offset:47936
	ds_read_b64_tr_b16 v[88:89], v133 offset:47968
	s_waitcnt lgkmcnt(6)
	v_mfma_f32_16x16x32_bf16 v[28:31], v[28:31], v[24:27], v[36:39]
	s_waitcnt lgkmcnt(4)
	v_mfma_f32_16x16x32_bf16 v[36:39], v[54:57], v[24:27], v[58:61]
	s_nop 2
	ds_read_b64_tr_b16 v[58:59], v133 offset:43648
	ds_read_b64_tr_b16 v[60:61], v133 offset:48000
	s_waitcnt lgkmcnt(3)
	v_mfma_f32_16x16x32_bf16 v[54:57], v[82:85], v[24:27], v[62:65]
	s_waitcnt lgkmcnt(2)
	v_mfma_f32_16x16x32_bf16 v[62:65], v[86:89], v[24:27], v[70:73]
	s_nop 2
	ds_read_b64_tr_b16 v[72:73], v133 offset:48032
	ds_read_b64_tr_b16 v[70:71], v133 offset:43680
	ds_read_b64_tr_b16 v[82:83], v133 offset:43712
	ds_read_b64_tr_b16 v[86:87], v133 offset:43744
	ds_read_b64_tr_b16 v[84:85], v133 offset:48064
	ds_read_b64_tr_b16 v[88:89], v133 offset:48096
	s_waitcnt lgkmcnt(6)
	v_mfma_f32_16x16x32_bf16 v[58:61], v[58:61], v[24:27], v[66:69]
	s_waitcnt lgkmcnt(4)
	v_mfma_f32_16x16x32_bf16 v[66:69], v[70:73], v[24:27], v[74:77]
	s_waitcnt lgkmcnt(1)
	v_mfma_f32_16x16x32_bf16 v[70:73], v[82:85], v[24:27], v[78:81]
	s_waitcnt lgkmcnt(0)
	v_mfma_f32_16x16x32_bf16 v[24:27], v[86:89], v[24:27], v[32:35]
	s_nop 2
	ds_read_b64_tr_b16 v[34:35], v133 offset:56576
	ds_read_b64_tr_b16 v[32:33], v133 offset:52224
	ds_read_b64_tr_b16 v[76:77], v133 offset:56608
	ds_read_b64_tr_b16 v[74:75], v133 offset:52256
	ds_read_b64_tr_b16 v[78:79], v133 offset:52288
	ds_read_b64_tr_b16 v[82:83], v133 offset:52320
	ds_read_b64_tr_b16 v[80:81], v133 offset:56640
	ds_read_b64_tr_b16 v[84:85], v133 offset:56672
	v_pk_mul_f32 v[14:15], v[14:15], v[8:9] op_sel_hi:[1,0]
	v_pk_mul_f32 v[10:11], v[10:11], v[8:9] op_sel_hi:[1,0]
	v_pk_mul_f32 v[22:23], v[22:23], v[8:9] op_sel_hi:[1,0]
	v_pk_mul_f32 v[12:13], v[12:13], v[8:9] op_sel_hi:[1,0]
	v_cvt_pk_bf16_f32 v10, v10, v11
	v_cvt_pk_bf16_f32 v11, v14, v15
	v_cvt_pk_bf16_f32 v12, v12, v13
	v_cvt_pk_bf16_f32 v13, v22, v23
	s_waitcnt lgkmcnt(6)
	s_nop 0
	v_mfma_f32_16x16x32_bf16 v[28:31], v[32:35], v[10:13], v[28:31]
	s_waitcnt lgkmcnt(4)
	v_mfma_f32_16x16x32_bf16 v[32:35], v[74:77], v[10:13], v[36:39]
	s_waitcnt lgkmcnt(1)
	v_mfma_f32_16x16x32_bf16 v[36:39], v[78:81], v[10:13], v[54:57]
	s_nop 2
	ds_read_b64_tr_b16 v[54:55], v133 offset:52352
	ds_read_b64_tr_b16 v[56:57], v133 offset:56704
	s_waitcnt lgkmcnt(2)
	v_mfma_f32_16x16x32_bf16 v[62:65], v[82:85], v[10:13], v[62:65]
	ds_read_b64_tr_b16 v[76:77], v133 offset:56736
	ds_read_b64_tr_b16 v[74:75], v133 offset:52384
	ds_read_b64_tr_b16 v[78:79], v133 offset:52416
	ds_read_b64_tr_b16 v[82:83], v133 offset:52448
	ds_read_b64_tr_b16 v[80:81], v133 offset:56768
	ds_read_b64_tr_b16 v[84:85], v133 offset:56800
	s_waitcnt lgkmcnt(6)
	v_mfma_f32_16x16x32_bf16 v[54:57], v[54:57], v[10:13], v[58:61]
	s_waitcnt lgkmcnt(4)
	v_mfma_f32_16x16x32_bf16 v[58:61], v[74:77], v[10:13], v[66:69]
	s_waitcnt lgkmcnt(1)
	v_mfma_f32_16x16x32_bf16 v[66:69], v[78:81], v[10:13], v[70:73]
	s_waitcnt lgkmcnt(0)
	v_mfma_f32_16x16x32_bf16 v[10:13], v[82:85], v[10:13], v[24:27]
	v_mul_f32_e64 v4, v4, v8
	v_mul_f32_e64 v5, v5, v8
	v_pk_mul_f32 v[0:1], v[0:1], v[8:9] op_sel_hi:[1,0]
	v_pk_mul_f32 v[14:15], v[6:7], v[8:9] op_sel_hi:[1,0]
	v_cvt_pk_bf16_f32 v0, v0, v1
	v_cvt_pk_bf16_f32 v1, v4, v5
	ds_read_b64_tr_b16 v[6:7], v133 offset:65280
	ds_read_b64_tr_b16 v[4:5], v133 offset:60928
	ds_read_b64_tr_b16 v[24:25], v133 offset:65312
	ds_read_b64_tr_b16 v[22:23], v133 offset:60960
	ds_read_b64_tr_b16 v[70:71], v133 offset:60992
	ds_read_b64_tr_b16 v[74:75], v133 offset:61024
	ds_read_b64_tr_b16 v[72:73], v133 offset:65344
	ds_read_b64_tr_b16 v[76:77], v133 offset:65376
	v_pk_mul_f32 v[2:3], v[2:3], v[8:9] op_sel_hi:[1,0]
	s_nop 0
	v_cvt_pk_bf16_f32 v2, v2, v3
	v_cvt_pk_bf16_f32 v3, v14, v15
	s_waitcnt lgkmcnt(6)
	s_nop 0
	v_mfma_f32_16x16x32_bf16 v[4:7], v[4:7], v[0:3], v[28:31]
	s_waitcnt lgkmcnt(4)
	v_mfma_f32_16x16x32_bf16 v[22:25], v[22:25], v[0:3], v[32:35]
	s_nop 0
	ds_read_b64_tr_b16 v[30:31], v133 offset:61056
	s_nop 0
	ds_read_b64_tr_b16 v[32:33], v133 offset:65408
	s_waitcnt lgkmcnt(3)
	v_mfma_f32_16x16x32_bf16 v[26:29], v[70:73], v[0:3], v[36:39]
	s_waitcnt lgkmcnt(2)
	v_mfma_f32_16x16x32_bf16 v[34:37], v[74:77], v[0:3], v[62:65]
	s_nop 2
	ds_read_b64_tr_b16 v[64:65], v133 offset:65440
	ds_read_b64_tr_b16 v[62:63], v133 offset:61088
	ds_read_b64_tr_b16 v[70:71], v133 offset:61120
	ds_read_b64_tr_b16 v[74:75], v133 offset:61152
	ds_read_b64_tr_b16 v[72:73], v133 offset:65472
	ds_read_b64_tr_b16 v[76:77], v133 offset:65504
	s_waitcnt lgkmcnt(6)
	v_mfma_f32_16x16x32_bf16 v[30:33], v[30:33], v[0:3], v[54:57]
	s_waitcnt lgkmcnt(4)
	v_mfma_f32_16x16x32_bf16 v[54:57], v[62:65], v[0:3], v[58:61]
	s_waitcnt lgkmcnt(1)
	v_mfma_f32_16x16x32_bf16 v[58:61], v[70:73], v[0:3], v[66:69]
	s_waitcnt lgkmcnt(0)
	v_mfma_f32_16x16x32_bf16 v[0:3], v[74:77], v[0:3], v[10:13]
	s_add_i32 s2, s2, -1
	v_lshl_add_u64 v[8:9], s[22:23], 0, v[18:19]
	v_cvt_pk_bf16_f32 v4, v4, v5
	v_cvt_pk_bf16_f32 v5, v6, v7
	s_nop 3
	v_cvt_pk_bf16_f32 v0, v0, v1
	v_cvt_pk_bf16_f32 v1, v2, v3
	v_lshl_add_u64 v[16:17], v[16:17], 0, s[18:19]
	v_lshl_add_u64 v[18:19], v[18:19], 0, s[24:25]
	v_lshl_add_u64 v[20:21], v[20:21], 0, s[24:25]
	s_cmp_eq_u32 s2, 0
	v_cvt_pk_bf16_f32 v6, v22, v23
	v_cvt_pk_bf16_f32 v7, v24, v25
	v_cvt_pk_bf16_f32 v10, v26, v27
	v_cvt_pk_bf16_f32 v11, v28, v29
	v_cvt_pk_bf16_f32 v12, v34, v35
	v_cvt_pk_bf16_f32 v13, v36, v37
	v_cvt_pk_bf16_f32 v14, v30, v31
	v_cvt_pk_bf16_f32 v15, v32, v33
	v_cvt_pk_bf16_f32 v22, v54, v55
	v_cvt_pk_bf16_f32 v23, v56, v57
	v_cvt_pk_bf16_f32 v24, v58, v59
	v_cvt_pk_bf16_f32 v25, v60, v61
	global_store_dwordx2 v[8:9], v[4:5], off offset:-128
	global_store_dwordx2 v[8:9], v[6:7], off offset:-96
	global_store_dwordx2 v[8:9], v[10:11], off offset:-64
	global_store_dwordx2 v[8:9], v[12:13], off offset:-32
	global_store_dwordx2 v[8:9], v[14:15], off
	global_store_dwordx2 v[8:9], v[22:23], off offset:32
	global_store_dwordx2 v[8:9], v[24:25], off offset:64
	global_store_dwordx2 v[8:9], v[0:1], off offset:96
	s_cbranch_scc0 .LBB0_1059
	s_branch .LBB0_1051
